# P5->P6 grid barrier replaced by per-panel arrival counters (CNT word 1), no L2 invalidate needed since OG is never read before P6
# speedup vs baseline: 1.0021x; 1.0021x over previous
; __device__ __forceinline__ int lane_id() { return (int)__builtin_amdgcn_mbcnt_hi(~0u, __builtin_amdgcn_mbcnt_lo(~0u, 0u)); }
; #define LAS __attribute__((address_space(3)))
; __device__ __forceinline__ s16x4 vtr(const LAS unsigned char* p) { return __builtin_bit_cast(s16x4, __builtin_amdgcn_ds_read_tr16_b64_v4i16((LAS s16x4*)p)); }
; __device__ __forceinline__ void attn_unit(LAS unsigned char* lds, const int wid, int b, int h, int qb, const bf16_t* __restrict__ Q, const bf16_t* __restrict__ K,
;                                           const bf16_t* __restrict__ V, const bf16_t* __restrict__ ZS, bf16_t* __restrict__ OG) {
;     ...
;     { const LAS unsigned char* vbp = lds + 32768 + vprev * 16384;
; #pragma unroll
;       for (int c = 0; c < 4; ++c)
; #pragma unroll
;           for (int s = 0; s < 4; ++s) {
;               const s16x4 lo = vtr(vbp + 4096 * s + vbase[0] + vcq[c]);
;               const s16x4 hh = vtr(vbp + 4096 * s + vbase[1] + vcq[c]);
;               const bf16x8 vfr = (bf16x8){lo[0], lo[1], lo[2], lo[3], hh[0], hh[1], hh[2], hh[3]};
;               o[c] = __builtin_amdgcn_mfma_f32_32x32x16_bf16(pa[s], vfr, o[c], 0, 0, 0);
;           } }
;     {
;         int lane_e = lane_id(); asm volatile("" : "+v"(lane_e));
;         const int r32e = lane_e & 31, hie = lane_e >> 5, rowq = lane_e >> 3, c8 = (lane_e & 7) * 8;
;         LAS float* stg = (LAS float*)(lds + 81920 + wid * 8192);
;         const size_t gbase = (tok0 + qw0) * DM + h * HD + c8;
;         u32x4 zv[2][4];
; #pragma unroll
;         for (int ps = 0; ps < 2; ++ps)
; #pragma unroll
;             for (int j = 0; j < 4; ++j) zv[ps][j] = *(const u32x4*)(ZS + gbase + (size_t)(8 * j + rowq) * DM + 64 * ps);
.LBB0_611:
	s_lshl_b32 s4, s71, 14
	s_add_i32 s4, s4, 0
	v_add_u32_e32 v112, s4, v188
	v_add_u32_e32 v113, s4, v189
	v_add_u32_e32 v86, v112, v190
	v_add_u32_e32 v94, v113, v190
	ds_read_b64_tr_b16 v[82:83], v94 offset:34816
	ds_read_b64_tr_b16 v[80:81], v86 offset:32768
	ds_read_b64_tr_b16 v[84:85], v86 offset:36864
	ds_read_b64_tr_b16 v[88:89], v86 offset:40960
	ds_read_b64_tr_b16 v[92:93], v86 offset:45056
	ds_read_b64_tr_b16 v[86:87], v94 offset:38912
	ds_read_b64_tr_b16 v[90:91], v94 offset:43008
	ds_read_b64_tr_b16 v[94:95], v94 offset:47104
	s_waitcnt lgkmcnt(6)
	v_mfma_f32_32x32x16_bf16 v[32:47], v[64:67], v[80:83], v[32:47]
	v_add_u32_e32 v82, v112, v191
	v_add_u32_e32 v98, v113, v191
	v_add_u32_e32 v102, v112, v192
	v_add_u32_e32 v110, v113, v192
	v_mov_b32_e32 v144, v195
	s_add_u32 s4, s50, s64
	s_addc_u32 s5, s51, 0
	s_waitcnt lgkmcnt(2)
	v_mfma_f32_32x32x16_bf16 v[32:47], v[68:71], v[84:87], v[32:47]
	s_lshl_b64 s[4:5], s[4:5], 11
	s_xor_b32 s7, s63, 0xf00
	s_add_i32 s63, s7, s54
	s_lshl_b32 s42, s62, 1
	s_mov_b32 m0, s55
	s_mov_b32 s64, 1
	s_mov_b32 s6, 2
	s_waitcnt lgkmcnt(1)
	v_mfma_f32_32x32x16_bf16 v[32:47], v[72:75], v[88:91], v[32:47]
	ds_read_b64_tr_b16 v[80:81], v82 offset:32768
	ds_read_b64_tr_b16 v[84:85], v82 offset:36864
	ds_read_b64_tr_b16 v[88:89], v82 offset:40960
	ds_read_b64_tr_b16 v[96:97], v82 offset:45056
	s_or_b32 s65, s63, 31
	s_add_i32 s66, s7, 0xff
	s_mov_b32 s67, 0
	s_mov_b32 s74, 0
	s_mov_b32 s32, 0
	s_mov_b32 s71, 0
	s_waitcnt lgkmcnt(4)
	v_mfma_f32_32x32x16_bf16 v[32:47], v[76:79], v[92:95], v[32:47]
	ds_read_b64_tr_b16 v[82:83], v98 offset:34816
	ds_read_b64_tr_b16 v[86:87], v98 offset:38912
	ds_read_b64_tr_b16 v[90:91], v98 offset:43008
	ds_read_b64_tr_b16 v[98:99], v98 offset:47104
	ds_read_b64_tr_b16 v[92:93], v102 offset:32768
	ds_read_b64_tr_b16 v[100:101], v102 offset:36864
	ds_read_b64_tr_b16 v[104:105], v102 offset:40960
	ds_read_b64_tr_b16 v[108:109], v102 offset:45056
	ds_read_b64_tr_b16 v[94:95], v110 offset:34816
	ds_read_b64_tr_b16 v[102:103], v110 offset:38912
	ds_read_b64_tr_b16 v[106:107], v110 offset:43008
	ds_read_b64_tr_b16 v[110:111], v110 offset:47104
	s_waitcnt lgkmcnt(11)
	v_mfma_f32_32x32x16_bf16 v[48:63], v[64:67], v[80:83], v[48:63]
	v_add_u32_e32 v80, v112, v193
	v_add_u32_e32 v81, v113, v193
	ds_read_b64_tr_b16 v[112:113], v80 offset:32768
	ds_read_b64_tr_b16 v[116:117], v80 offset:36864
	ds_read_b64_tr_b16 v[120:121], v80 offset:40960
	ds_read_b64_tr_b16 v[124:125], v80 offset:45056
	ds_read_b64_tr_b16 v[114:115], v81 offset:34816
	ds_read_b64_tr_b16 v[118:119], v81 offset:38912
	ds_read_b64_tr_b16 v[122:123], v81 offset:43008
	ds_read_b64_tr_b16 v[126:127], v81 offset:47104
	v_mov_b32_e32 v81, s5
	v_lshlrev_b32_e32 v80, 3, v144
	s_waitcnt lgkmcnt(14)
	v_mfma_f32_32x32x16_bf16 v[48:63], v[68:71], v[84:87], v[48:63]
	v_and_b32_e32 v149, 56, v80
	v_or_b32_e32 v80, s4, v149
	v_ashrrev_i32_e32 v132, 3, v144
	v_or_b32_e32 v80, s62, v80
	v_lshlrev_b64 v[134:135], 1, v[80:81]
	v_ashrrev_i32_e32 v133, 31, v132
	v_lshl_add_u64 v[80:81], s[46:47], 0, v[134:135]
	v_lshlrev_b64 v[136:137], 12, v[132:133]
	v_lshl_add_u64 v[82:83], v[80:81], 0, v[136:137]
	v_mfma_f32_32x32x16_bf16 v[48:63], v[72:75], v[88:91], v[48:63]
	global_load_dwordx4 v[88:91], v[82:83], off
	v_add_u32_e32 v138, 8, v132
	v_ashrrev_i32_e32 v139, 31, v138
	v_lshlrev_b64 v[140:141], 12, v[138:139]
	v_lshl_add_u64 v[84:85], v[80:81], 0, v[140:141]
	v_add_u32_e32 v142, 16, v132
	v_add_u32_e32 v160, 24, v132
	s_waitcnt lgkmcnt(11)
	v_mfma_f32_32x32x16_bf16 v[0:15], v[64:67], v[92:95], v[0:15]
	global_load_dwordx4 v[92:95], v[84:85], off
	v_ashrrev_i32_e32 v143, 31, v142
	v_ashrrev_i32_e32 v161, 31, v160
	v_lshlrev_b64 v[158:159], 12, v[142:143]
	v_lshlrev_b64 v[162:163], 12, v[160:161]
	v_lshl_add_u64 v[86:87], v[80:81], 0, v[158:159]
	v_lshl_add_u64 v[80:81], v[80:81], 0, v[162:163]
	s_waitcnt lgkmcnt(10)
	v_mfma_f32_32x32x16_bf16 v[0:15], v[68:71], v[100:103], v[0:15]
	v_and_b32_e32 v133, 31, v144
	v_lshlrev_b32_e32 v133, 2, v133
	v_readlane_b32 s4, v248, 25
	v_readlane_b32 s5, v248, 26
	v_mov_b32_e32 v143, 0
	v_mov_b32_e32 v139, 0
	v_mfma_f32_32x32x16_bf16 v[48:63], v[76:79], v[96:99], v[48:63]
	global_load_dwordx4 v[96:99], v[82:83], off offset:128
	s_waitcnt lgkmcnt(9)
	v_mfma_f32_32x32x16_bf16 v[0:15], v[72:75], v[104:107], v[0:15]
	global_load_dwordx4 v[100:103], v[84:85], off offset:128
	global_load_dwordx4 v[104:107], v[86:87], off
	s_nop 0
	global_load_dwordx4 v[84:87], v[86:87], off offset:128
	s_nop 0
	global_load_dwordx4 v[128:131], v[80:81], off
	s_nop 0
	global_load_dwordx4 v[80:83], v[80:81], off offset:128
	s_waitcnt lgkmcnt(8)
	v_mfma_f32_32x32x16_bf16 v[0:15], v[76:79], v[108:111], v[0:15]
	v_lshlrev_b32_e32 v110, 5, v144
	v_and_b32_e32 v110, 0xfffffc00, v110
	v_add3_u32 v110, s56, v133, v110
	ds_write2_b32 v110, v32, v48 offset1:32
	ds_write2_b32 v110, v33, v49 offset0:64 offset1:96
	ds_write2_b32 v110, v34, v50 offset0:128 offset1:160
	ds_write2_b32 v110, v35, v51 offset0:192 offset1:224
	v_add_u32_e32 v48, 0x800, v110
	v_add_u32_e32 v49, 0x1000, v110
	v_add_u32_e32 v50, 0x1800, v110
	v_lshl_add_u32 v108, v149, 2, s56
	ds_write2_b32 v48, v36, v52 offset1:32
	ds_write2_b32 v48, v37, v53 offset0:64 offset1:96
	ds_write2_b32 v48, v38, v54 offset0:128 offset1:160
	ds_write2_b32 v48, v39, v55 offset0:192 offset1:224
	ds_write2_b32 v49, v40, v56 offset1:32
	ds_write2_b32 v49, v41, v57 offset0:64 offset1:96
	ds_write2_b32 v49, v42, v58 offset0:128 offset1:160
	ds_write2_b32 v49, v43, v59 offset0:192 offset1:224
	ds_write2_b32 v50, v44, v60 offset1:32
	ds_write2_b32 v50, v45, v61 offset0:64 offset1:96
	ds_write2_b32 v50, v46, v62 offset0:128 offset1:160
	ds_write2_b32 v50, v47, v63 offset0:192 offset1:224
	v_lshl_add_u32 v109, v132, 8, v108
	s_waitcnt lgkmcnt(0)
; #define LAS __attribute__((address_space(3)))
; __device__ __forceinline__ unsigned pk_bf16(float lo, float hi) { return pg8::cvt_pk_bf16(lo, hi); }
; __device__ __forceinline__ float bf_lo(unsigned w) { return __uint_as_float(w << 16); }
; __device__ __forceinline__ float bf_hi(unsigned w) { return __uint_as_float(w & 0xffff0000u); }
; __device__ __forceinline__ int crow(int r, int hi) { return (r & 3) + 8 * (r >> 2) + 4 * hi; }
; __device__ __forceinline__ void attn_unit(LAS unsigned char* lds, const int wid, int b, int h, int qb, const bf16_t* __restrict__ Q, const bf16_t* __restrict__ K,
;                                           const bf16_t* __restrict__ V, const bf16_t* __restrict__ ZS, bf16_t* __restrict__ OG) {
;     ...
;         for (int ps = 0; ps < 2; ++ps) {
; #pragma unroll
;             for (int r = 0; r < 16; ++r) {
;                 stg[crow(r, hie) * 64 + r32e] = o[2 * ps][r];
;                 stg[crow(r, hie) * 64 + 32 + r32e] = o[2 * ps + 1][r];
;             }
;             asm volatile("s_waitcnt lgkmcnt(0)" ::: "memory");
; #pragma unroll
;             for (int j = 0; j < 4; ++j) {
;                 const f32x4 oa = *(const LAS f32x4*)(stg + (8 * j + rowq) * 64 + c8), ob = *(const LAS f32x4*)(stg + (8 * j + rowq) * 64 + c8 + 4);
;                 const u32x4 z = zv[ps][j];
;                 u32x4 w; w.x = pk_bf16(oa[0] * bf_lo(z.x), oa[1] * bf_hi(z.x)); w.y = pk_bf16(oa[2] * bf_lo(z.y), oa[3] * bf_hi(z.y));
;                 w.z = pk_bf16(ob[0] * bf_lo(z.z), ob[1] * bf_hi(z.z)); w.w = pk_bf16(ob[2] * bf_lo(z.w), ob[3] * bf_hi(z.w));
;                 *(u32x4*)(OG + gbase + (size_t)(8 * j + rowq) * DM + 64 * ps) = w;
;             }
;             asm volatile("s_waitcnt lgkmcnt(0)" ::: "memory");
;         }
	ds_read_b128 v[32:35], v109
	ds_read_b128 v[36:39], v109 offset:16
	v_lshl_add_u32 v51, v138, 8, v108
	v_lshl_add_u64 v[40:41], s[4:5], 0, v[134:135]
	s_waitcnt lgkmcnt(14)
	v_mfma_f32_32x32x16_bf16 v[16:31], v[64:67], v[112:115], v[16:31]
	v_lshl_add_u32 v52, v142, 8, v108
	v_lshl_add_u32 v53, v160, 8, v108
	v_or_b32_e32 v144, s63, v178
	v_mov_b32_e32 v149, v145
	s_add_i32 s4, s7, 0x100
	s_lshr_b32 s8, s4, 6
	v_mov_b32_e32 v142, 0
	v_mfma_f32_32x32x16_bf16 v[16:31], v[68:71], v[116:119], v[16:31]
	v_mov_b32_e32 v138, 0
	v_mov_b32_e32 v132, 0
	v_mov_b32_e32 v133, 0
	v_mov_b32_e32 v134, 0
	v_mov_b32_e32 v135, 0
	s_waitcnt vmcnt(7)
	v_lshlrev_b32_e32 v42, 16, v88
	s_waitcnt lgkmcnt(1)
	v_mul_f32_e32 v32, v32, v42
	v_and_b32_e32 v42, 0xffff0000, v88
	v_mul_f32_e32 v33, v33, v42
	v_cvt_pk_bf16_f32 v32, v32, v33
	v_lshlrev_b32_e32 v33, 16, v89
	v_mul_f32_e32 v33, v34, v33
	v_and_b32_e32 v34, 0xffff0000, v89
	v_mul_f32_e32 v34, v35, v34
	v_cvt_pk_bf16_f32 v33, v33, v34
	v_lshlrev_b32_e32 v34, 16, v90
	v_and_b32_e32 v35, 0xffff0000, v90
	s_waitcnt lgkmcnt(0)
	v_mul_f32_e32 v34, v36, v34
	v_mul_f32_e32 v35, v37, v35
	v_cvt_pk_bf16_f32 v34, v34, v35
	v_lshlrev_b32_e32 v35, 16, v91
	v_and_b32_e32 v36, 0xffff0000, v91
	v_mul_f32_e32 v35, v38, v35
	v_mul_f32_e32 v36, v39, v36
	v_cvt_pk_bf16_f32 v35, v35, v36
	ds_read_b128 v[36:39], v51
	v_lshl_add_u64 v[42:43], v[40:41], 0, v[136:137]
	s_waitcnt vmcnt(6)
	v_lshlrev_b32_e32 v44, 16, v92
	global_store_dwordx4 v[42:43], v[32:35], off sc1
	ds_read_b128 v[32:35], v51 offset:16
	s_waitcnt lgkmcnt(1)
	v_mul_f32_e32 v36, v36, v44
	v_and_b32_e32 v44, 0xffff0000, v92
	v_mul_f32_e32 v37, v37, v44
	v_cvt_pk_bf16_f32 v36, v36, v37
	v_lshlrev_b32_e32 v37, 16, v93
	v_mul_f32_e32 v37, v38, v37
	v_and_b32_e32 v38, 0xffff0000, v93
	v_mul_f32_e32 v38, v39, v38
	v_cvt_pk_bf16_f32 v37, v37, v38
	v_lshlrev_b32_e32 v38, 16, v94
	s_waitcnt lgkmcnt(0)
	v_mul_f32_e32 v32, v32, v38
	v_and_b32_e32 v38, 0xffff0000, v94
	v_mul_f32_e32 v33, v33, v38
	v_cvt_pk_bf16_f32 v38, v32, v33
	v_lshlrev_b32_e32 v32, 16, v95
	v_and_b32_e32 v33, 0xffff0000, v95
	v_mul_f32_e32 v32, v34, v32
	v_mul_f32_e32 v33, v35, v33
	v_cvt_pk_bf16_f32 v39, v32, v33
	ds_read_b128 v[32:35], v52
	v_lshl_add_u64 v[44:45], v[40:41], 0, v[140:141]
	s_waitcnt vmcnt(4)
	v_lshlrev_b32_e32 v46, 16, v104
	global_store_dwordx4 v[44:45], v[36:39], off sc1
	ds_read_b128 v[36:39], v52 offset:16
	s_waitcnt lgkmcnt(1)
	v_mul_f32_e32 v32, v32, v46
	v_and_b32_e32 v46, 0xffff0000, v104
	v_mul_f32_e32 v33, v33, v46
	v_cvt_pk_bf16_f32 v32, v32, v33
	v_lshlrev_b32_e32 v33, 16, v105
	v_mul_f32_e32 v33, v34, v33
	v_and_b32_e32 v34, 0xffff0000, v105
	v_mul_f32_e32 v34, v35, v34
	v_cvt_pk_bf16_f32 v33, v33, v34
	v_lshlrev_b32_e32 v34, 16, v106
	v_and_b32_e32 v35, 0xffff0000, v106
	s_waitcnt lgkmcnt(0)
	v_mul_f32_e32 v34, v36, v34
	v_mul_f32_e32 v35, v37, v35
	v_cvt_pk_bf16_f32 v34, v34, v35
	v_lshlrev_b32_e32 v35, 16, v107
	v_and_b32_e32 v36, 0xffff0000, v107
	v_mul_f32_e32 v35, v38, v35
	v_mul_f32_e32 v36, v39, v36
	v_cvt_pk_bf16_f32 v35, v35, v36
	ds_read_b128 v[36:39], v53
	v_mfma_f32_32x32x16_bf16 v[16:31], v[72:75], v[120:123], v[16:31]
	v_lshl_add_u64 v[46:47], v[40:41], 0, v[158:159]
	s_waitcnt vmcnt(3)
	v_lshlrev_b32_e32 v54, 16, v128
	global_store_dwordx4 v[46:47], v[32:35], off sc1
	ds_read_b128 v[32:35], v53 offset:16
	s_waitcnt lgkmcnt(1)
	v_mul_f32_e32 v36, v36, v54
	v_and_b32_e32 v54, 0xffff0000, v128
	v_mul_f32_e32 v37, v37, v54
	v_cvt_pk_bf16_f32 v36, v36, v37
	v_lshlrev_b32_e32 v37, 16, v129
	v_mul_f32_e32 v37, v38, v37
	v_and_b32_e32 v38, 0xffff0000, v129
	v_mfma_f32_32x32x16_bf16 v[16:31], v[76:79], v[124:127], v[16:31]
	v_mul_f32_e32 v38, v39, v38
	v_cvt_pk_bf16_f32 v37, v37, v38
	v_lshlrev_b32_e32 v38, 16, v130
	s_waitcnt lgkmcnt(0)
	v_mul_f32_e32 v32, v32, v38
	v_and_b32_e32 v38, 0xffff0000, v130
	v_mul_f32_e32 v33, v33, v38
	v_cvt_pk_bf16_f32 v38, v32, v33
	v_lshlrev_b32_e32 v32, 16, v131
	v_and_b32_e32 v33, 0xffff0000, v131
	v_mul_f32_e32 v32, v34, v32
	v_mul_f32_e32 v33, v35, v33
	v_cvt_pk_bf16_f32 v39, v32, v33
	v_lshl_add_u64 v[32:33], v[40:41], 0, v[162:163]
	global_store_dwordx4 v[32:33], v[36:39], off sc1
	s_waitcnt lgkmcnt(0)
	ds_write2_b32 v110, v0, v16 offset1:32
	ds_write2_b32 v110, v1, v17 offset0:64 offset1:96
	ds_write2_b32 v110, v2, v18 offset0:128 offset1:160
	ds_write2_b32 v110, v3, v19 offset0:192 offset1:224
	ds_write2_b32 v48, v4, v20 offset1:32
	ds_write2_b32 v48, v5, v21 offset0:64 offset1:96
	ds_write2_b32 v48, v6, v22 offset0:128 offset1:160
	ds_write2_b32 v48, v7, v23 offset0:192 offset1:224
	ds_write2_b32 v49, v8, v24 offset1:32
	ds_write2_b32 v49, v9, v25 offset0:64 offset1:96
	ds_write2_b32 v49, v10, v26 offset0:128 offset1:160
	ds_write2_b32 v49, v11, v27 offset0:192 offset1:224
	ds_write2_b32 v50, v12, v28 offset1:32
	ds_write2_b32 v50, v13, v29 offset0:64 offset1:96
	ds_write2_b32 v50, v14, v30 offset0:128 offset1:160
	ds_write2_b32 v50, v15, v31 offset0:192 offset1:224
	s_waitcnt lgkmcnt(0)
	ds_read_b128 v[0:3], v109
	ds_read_b128 v[4:7], v109 offset:16
	v_lshlrev_b32_e32 v8, 16, v96
	v_mov_b32_e32 v34, v145
	v_mov_b32_e32 v35, v145
	s_waitcnt lgkmcnt(1)
	v_mul_f32_e32 v0, v0, v8
	v_and_b32_e32 v8, 0xffff0000, v96
	v_mul_f32_e32 v1, v1, v8
	v_cvt_pk_bf16_f32 v0, v0, v1
	v_lshlrev_b32_e32 v1, 16, v97
	v_mul_f32_e32 v1, v2, v1
	v_and_b32_e32 v2, 0xffff0000, v97
	v_mul_f32_e32 v2, v3, v2
	v_cvt_pk_bf16_f32 v1, v1, v2
	v_lshlrev_b32_e32 v2, 16, v98
	v_and_b32_e32 v3, 0xffff0000, v98
	s_waitcnt lgkmcnt(0)
; #define LAS __attribute__((address_space(3)))
; __device__ __forceinline__ unsigned pk_bf16(float lo, float hi) { return pg8::cvt_pk_bf16(lo, hi); }
; #define tid tid_of(wave)
; __device__ __forceinline__ void attn_unit(LAS unsigned char* lds, const int wid, int b, int h, int qb, const bf16_t* __restrict__ Q, const bf16_t* __restrict__ K,
;                                           const bf16_t* __restrict__ V, const bf16_t* __restrict__ ZS, bf16_t* __restrict__ OG) {
;     ...
;     { const bf16_t* qp = Q + (tok0 + qabs) * DM + h * HD + 8 * hi;
; #pragma unroll
;       for (int d0 = 0; d0 < 8; ++d0) qf[d0] = *(const bf16x8*)(qp + 16 * d0); }
;     f32x16 o[4];
; #pragma unroll
;     for (int c = 0; c < 4; ++c)
; #pragma unroll
;         for (int r = 0; r < 16; ++r) o[c][r] = 0.f;
;     bf16x8 pa[4];
; #pragma unroll
;     for (int s = 0; s < 4; ++s) pa[s] = (bf16x8){0, 0, 0, 0, 0, 0, 0, 0};
;     float carry = 0.f;
;     const int NT = (q0 + 256) / 64;
;     const int srow = tid >> 4, sch = (tid & 15) ^ (((srow & 3) << 2) | ((srow >> 2) & 3));
;     const bf16_t* kg = K + (tok0 + srow) * DM + h * HD + sch * 8;
;     const bf16_t* vg = V + (tok0 + srow) * DM + h * HD + sch * 8;
;     LAS unsigned char* ldsw = lds + wid * 1024;
;     ...
;     ATT_STAGE(NT - 1, 0, 32768);
;     asm volatile("s_waitcnt vmcnt(0)" ::: "memory");
;     __syncthreads();
;     ...
;         for (int ps = 0; ps < 2; ++ps) {
; #pragma unroll
;             for (int r = 0; r < 16; ++r) {
;                 stg[crow(r, hie) * 64 + r32e] = o[2 * ps][r];
;                 stg[crow(r, hie) * 64 + 32 + r32e] = o[2 * ps + 1][r];
;             }
;             asm volatile("s_waitcnt lgkmcnt(0)" ::: "memory");
; #pragma unroll
;             for (int j = 0; j < 4; ++j) {
;                 const f32x4 oa = *(const LAS f32x4*)(stg + (8 * j + rowq) * 64 + c8), ob = *(const LAS f32x4*)(stg + (8 * j + rowq) * 64 + c8 + 4);
;                 const u32x4 z = zv[ps][j];
;                 u32x4 w; w.x = pk_bf16(oa[0] * bf_lo(z.x), oa[1] * bf_hi(z.x)); w.y = pk_bf16(oa[2] * bf_lo(z.y), oa[3] * bf_hi(z.y));
;                 w.z = pk_bf16(ob[0] * bf_lo(z.z), ob[1] * bf_hi(z.z)); w.w = pk_bf16(ob[2] * bf_lo(z.w), ob[3] * bf_hi(z.w));
;                 *(u32x4*)(OG + gbase + (size_t)(8 * j + rowq) * DM + 64 * ps) = w;
;             }
;             asm volatile("s_waitcnt lgkmcnt(0)" ::: "memory");
;         }
	v_mul_f32_e32 v2, v4, v2
	v_mul_f32_e32 v3, v5, v3
	v_cvt_pk_bf16_f32 v2, v2, v3
	v_lshlrev_b32_e32 v3, 16, v99
	v_and_b32_e32 v4, 0xffff0000, v99
	v_mul_f32_e32 v3, v6, v3
	v_mul_f32_e32 v4, v7, v4
	v_cvt_pk_bf16_f32 v3, v3, v4
	ds_read_b128 v[4:7], v51
	v_lshlrev_b32_e32 v8, 16, v100
	global_store_dwordx4 v[42:43], v[0:3], off offset:128 sc1
	ds_read_b128 v[0:3], v51 offset:16
	v_mov_b32_e32 v36, v145
	s_waitcnt lgkmcnt(1)
	v_mul_f32_e32 v4, v4, v8
	v_and_b32_e32 v8, 0xffff0000, v100
	v_mul_f32_e32 v5, v5, v8
	v_cvt_pk_bf16_f32 v4, v4, v5
	v_lshlrev_b32_e32 v5, 16, v101
	v_mul_f32_e32 v5, v6, v5
	v_and_b32_e32 v6, 0xffff0000, v101
	v_mul_f32_e32 v6, v7, v6
	v_cvt_pk_bf16_f32 v5, v5, v6
	v_lshlrev_b32_e32 v6, 16, v102
	s_waitcnt lgkmcnt(0)
	v_mul_f32_e32 v0, v0, v6
	v_and_b32_e32 v6, 0xffff0000, v102
	v_mul_f32_e32 v1, v1, v6
	v_cvt_pk_bf16_f32 v6, v0, v1
	v_lshlrev_b32_e32 v0, 16, v103
	v_and_b32_e32 v1, 0xffff0000, v103
	v_mul_f32_e32 v0, v2, v0
	v_mul_f32_e32 v1, v3, v1
	v_cvt_pk_bf16_f32 v7, v0, v1
	ds_read_b128 v[0:3], v52
	v_lshlrev_b32_e32 v8, 16, v84
	global_store_dwordx4 v[44:45], v[4:7], off offset:128 sc1
	ds_read_b128 v[4:7], v52 offset:16
	v_mov_b32_e32 v37, v145
	s_waitcnt lgkmcnt(1)
	v_mul_f32_e32 v0, v0, v8
	v_and_b32_e32 v8, 0xffff0000, v84
	v_mul_f32_e32 v1, v1, v8
	v_cvt_pk_bf16_f32 v0, v0, v1
	v_lshlrev_b32_e32 v1, 16, v85
	v_mul_f32_e32 v1, v2, v1
	v_and_b32_e32 v2, 0xffff0000, v85
	v_mul_f32_e32 v2, v3, v2
	v_cvt_pk_bf16_f32 v1, v1, v2
	v_lshlrev_b32_e32 v2, 16, v86
	v_and_b32_e32 v3, 0xffff0000, v86
	s_waitcnt lgkmcnt(0)
	v_mul_f32_e32 v2, v4, v2
	v_mul_f32_e32 v3, v5, v3
	v_cvt_pk_bf16_f32 v2, v2, v3
	v_lshlrev_b32_e32 v3, 16, v87
	v_and_b32_e32 v4, 0xffff0000, v87
	v_mul_f32_e32 v3, v6, v3
	v_mul_f32_e32 v4, v7, v4
	v_cvt_pk_bf16_f32 v3, v3, v4
	ds_read_b128 v[4:7], v53
	s_waitcnt vmcnt(6)
	v_lshlrev_b32_e32 v8, 16, v80
	global_store_dwordx4 v[46:47], v[0:3], off offset:128 sc1
	ds_read_b128 v[0:3], v53 offset:16
	v_mov_b32_e32 v46, v145
	s_waitcnt lgkmcnt(1)
	v_mul_f32_e32 v4, v4, v8
	v_and_b32_e32 v8, 0xffff0000, v80
	v_mul_f32_e32 v5, v5, v8
	v_cvt_pk_bf16_f32 v4, v4, v5
	v_lshlrev_b32_e32 v5, 16, v81
	v_mul_f32_e32 v5, v6, v5
	v_and_b32_e32 v6, 0xffff0000, v81
	v_mul_f32_e32 v6, v7, v6
	v_cvt_pk_bf16_f32 v5, v5, v6
	v_lshlrev_b32_e32 v6, 16, v82
	s_waitcnt lgkmcnt(0)
	v_mul_f32_e32 v0, v0, v6
	v_and_b32_e32 v6, 0xffff0000, v82
	v_mul_f32_e32 v1, v1, v6
	v_cvt_pk_bf16_f32 v6, v0, v1
	v_lshlrev_b32_e32 v0, 16, v83
	v_and_b32_e32 v1, 0xffff0000, v83
	v_mul_f32_e32 v0, v2, v0
	v_mul_f32_e32 v1, v3, v1
	v_cvt_pk_bf16_f32 v7, v0, v1
	v_lshl_add_u64 v[0:1], s[50:51], 0, v[144:145]
	v_lshlrev_b64 v[0:1], 12, v[0:1]
	v_lshl_add_u64 v[0:1], s[92:93], 0, v[0:1]
	v_lshl_add_u64 v[0:1], v[0:1], 0, s[42:43]
	global_store_dwordx4 v[32:33], v[4:7], off offset:128 sc1
	v_lshl_add_u64 v[0:1], v[0:1], 0, v[148:149]
	s_waitcnt lgkmcnt(0)
	s_barrier
	global_load_dwordx4 v[96:99], v[0:1], off
	global_load_dwordx4 v[100:103], v[0:1], off offset:32
	global_load_dwordx4 v[104:107], v[0:1], off offset:64
	global_load_dwordx4 v[108:111], v[0:1], off offset:96
	global_load_dwordx4 v[112:115], v[0:1], off offset:128
	global_load_dwordx4 v[116:119], v[0:1], off offset:160
	global_load_dwordx4 v[120:123], v[0:1], off offset:192
	global_load_dwordx4 v[124:127], v[0:1], off offset:224
	s_add_i32 s42, s8, -1
	s_lshl_b64 s[4:5], s[42:43], 18
	v_lshl_add_u64 v[0:1], v[154:155], 0, s[4:5]
	global_load_lds_dwordx4 v[0:1], off
	v_lshl_add_u64 v[0:1], v[0:1], 0, s[48:49]
	s_mov_b32 m0, s59
	v_mov_b32_e32 v32, v145
	global_load_lds_dwordx4 v[0:1], off
	v_lshl_add_u64 v[0:1], v[156:157], 0, s[4:5]
	s_mov_b32 m0, s60
	v_mov_b32_e32 v33, v145
	global_load_lds_dwordx4 v[0:1], off
	v_lshl_add_u64 v[0:1], v[0:1], 0, s[48:49]
	s_mov_b32 m0, s61
	v_mov_b32_e32 v47, v145
	global_load_lds_dwordx4 v[0:1], off
	s_waitcnt vmcnt(0)
	v_mov_b32_e32 v38, v145
	v_mov_b32_e32 v39, v145
	v_mov_b32_e32 v40, v145
	v_mov_b32_e32 v41, v145
	v_mov_b32_e32 v42, v145
	v_mov_b32_e32 v43, v145
	v_mov_b32_e32 v44, v145
	v_mov_b32_e32 v45, v145
	v_mov_b64_e32 v[62:63], v[46:47]
	v_mov_b64_e32 v[0:1], v[32:33]
	v_mov_b64_e32 v[16:17], v[32:33]
	s_add_i32 s42, s8, -2
	v_mov_b32_e32 v158, 0
	s_mov_b64 s[4:5], 0
	v_mov_b32_e32 v140, 0
	v_mov_b32_e32 v141, 0
	v_mov_b32_e32 v136, 0
	v_mov_b32_e32 v137, 0
	v_mov_b32_e32 v128, 0
	v_mov_b32_e32 v129, 0
	v_mov_b32_e32 v130, 0
	v_mov_b32_e32 v131, 0
	v_mov_b64_e32 v[60:61], v[44:45]
	v_mov_b64_e32 v[58:59], v[42:43]
	v_mov_b64_e32 v[56:57], v[40:41]
	v_mov_b64_e32 v[54:55], v[38:39]
	v_mov_b64_e32 v[52:53], v[36:37]
	v_mov_b64_e32 v[50:51], v[34:35]
	v_mov_b64_e32 v[48:49], v[32:33]
	v_mov_b64_e32 v[2:3], v[34:35]
	v_mov_b64_e32 v[4:5], v[36:37]
	v_mov_b64_e32 v[6:7], v[38:39]
	v_mov_b64_e32 v[8:9], v[40:41]
	v_mov_b64_e32 v[10:11], v[42:43]
	v_mov_b64_e32 v[12:13], v[44:45]
	v_mov_b64_e32 v[14:15], v[46:47]
	v_mov_b64_e32 v[18:19], v[34:35]
	v_mov_b64_e32 v[20:21], v[36:37]
	v_mov_b64_e32 v[22:23], v[38:39]
	v_mov_b64_e32 v[24:25], v[40:41]
	v_mov_b64_e32 v[26:27], v[42:43]
	v_mov_b64_e32 v[28:29], v[44:45]
	v_mov_b64_e32 v[30:31], v[46:47]
	s_waitcnt vmcnt(0) lgkmcnt(0)
	s_barrier
	s_sub_i32 s98, s63, s54
	s_xor_b32 s98, s98, 0xf00
	s_add_i32 s98, s98, s50
	s_lshr_b32 s98, s98, 8
	s_lshl_b32 s98, s98, 8
	s_add_i32 s98, s98, 4
	v_mov_b32_e32 v236, s98
	v_mov_b32_e32 v237, 1
	s_add_u32 s98, s82, 0x310000
	s_addc_u32 s99, s83, 0
	s_mov_b64 s[100:101], exec
	s_mov_b64 exec, 1
	global_atomic_add v236, v237, s[98:99]
	s_mov_b64 exec, s[100:101]
	s_mov_b32 s72, s6
	s_cmp_lg_u32 s42, -1
	s_mov_b64 s[6:7], -1
	s_cbranch_scc0 .LBB0_613

; __device__ __forceinline__ void attn_phase(LAS unsigned char* lds, const int wid_, int vcu, int G, const bf16_t* Q, const bf16_t* K, const bf16_t* V, const bf16_t* ZS, bf16_t* OG) {
;     ...
;         attn_unit(lds, wid_, bh >> 4, bh & 15, s, Q, K, V, ZS, OG);
;         attn_unit(lds, wid_, bh >> 4, bh & 15, 15 - s, Q, K, V, ZS, OG);
.LBB0_628:
	s_waitcnt vmcnt(0)
	s_sub_i32 s98, s63, s54
	s_add_i32 s98, s98, s50
	s_lshr_b32 s98, s98, 8
	s_lshl_b32 s98, s98, 8
	s_add_i32 s98, s98, 4
	v_mov_b32_e32 v236, s98
	v_mov_b32_e32 v237, 1
	s_add_u32 s98, s82, 0x310000
	s_addc_u32 s99, s83, 0
	s_mov_b64 s[100:101], exec
	s_mov_b64 exec, 1
	global_atomic_add v236, v237, s[98:99]
	s_mov_b64 exec, s[100:101]
	s_mov_b32 s67, s84

; __device__ __forceinline__ int tid_of(int wave) { return wave * 64 + lane_id(); }
; #define SEAM(k) do { if (IN(k) && IN((k) + 1)) xcd_barrier(bar); } while (0)
; __device__ __forceinline__ void xcd_barrier(const XcdBarrier& b) {
;     asm volatile("s_waitcnt vmcnt(0)" ::: "memory");
;     __syncthreads();
;     if (tid_of(b.w) == 0) {
;         unsigned* bar = b.bar;
;         __builtin_amdgcn_s_waitcnt(0);
;         unsigned nloc = b.st[0], nx = b.st[1];
;         if (nloc == 0u) { xcd_barrier_complete(bar, b.x, nloc, nx); b.st[0] = nloc; b.st[1] = nx; }
; __global__ void __launch_bounds__(NWAVES * 64, 2) fwd_kernel(Args a) {
;     ...
;     SEAM(5);
.LBB0_630:
	v_readlane_b32 s4, v248, 0
	v_readlane_b32 s5, v248, 1
	s_cmp_gt_i32 s5, 6
	s_cselect_b64 s[0:1], -1, 0
	s_and_b64 s[4:5], s[40:41], s[0:1]
	v_readlane_b32 s62, v248, 33
	s_andn2_b64 vcc, exec, s[4:5]
	v_readlane_b32 s63, v248, 34
	v_readlane_b32 s6, v248, 2
	v_readlane_b32 s7, v248, 3
	s_cmpk_eq_i32 s88, 0x100
	s_cbranch_scc1 .LBB0_684
	s_cbranch_vccnz .LBB0_684
	s_waitcnt vmcnt(0)
	s_waitcnt vmcnt(0) lgkmcnt(0)
	s_barrier
	s_and_saveexec_b64 s[4:5], s[76:77]
	s_cbranch_execz .LBB0_683
	s_add_i32 s2, 0, 0x24fe0
	v_mov_b32_e32 v0, s2
	s_waitcnt vmcnt(0) expcnt(0) lgkmcnt(0)
	ds_read_b32 v2, v0
	s_add_i32 s2, 0, 0x24fe4
	v_mov_b32_e32 v0, s2
	ds_read_b32 v0, v0
	s_waitcnt lgkmcnt(1)
	v_cmp_ne_u32_e32 vcc, 0, v2
	s_cbranch_vccnz .LBB0_647
	s_add_u32 s6, s68, 0x1000
	s_addc_u32 s7, s69, 0
	s_add_u32 s8, s68, 0x1100
	s_addc_u32 s9, s69, 0
	s_add_u32 s10, s68, 0x1200
	s_addc_u32 s11, s69, 0
	s_mul_i32 s2, s89, s90
	s_add_u32 s12, s68, 0x1300
	s_mul_i32 s2, s2, s88
	s_addc_u32 s13, s69, 0
	s_mov_b32 s20, 1
	v_mov_b32_e32 v16, 0
	s_branch .LBB0_635

; #define PG8_STAGE(bufoff, gbase, voff) do { _Pragma("unroll") for (int _i = 0; _i < 2; ++_i) \
;         __builtin_amdgcn_global_load_lds((const unsigned*)((const char*)(gbase) + (voff)[_i]), (PG8_LAS unsigned*)(lds + (bufoff) + ldsw + _i * 8192), 16, 0, 0); } while (0)
; #define PG8_WAIT_V(n) asm volatile("s_waitcnt vmcnt(" #n ")" ::: "memory")
; #define PG8_BAR __builtin_amdgcn_s_barrier()
; template <class Epi, class Sched, bool ALIGN_EPI = false, bool SP2 = false>
; __device__ __forceinline__ void gemm_phase(PG8_LAS unsigned char* lds, const Gemm g, const Sched& S, const Epi& E, const int wave_) {
;     ...
;     const char* cA = (const char*)g.A + (size_t)cur.pm * tstep; const char* cB = (const char*)g.Bt + (size_t)cur.pn * tstep;
;     S.a_ready(cur);
;     if constexpr (SP2) {
;         PG8_STAGE(PG8_SB(0, 0), cB, voffB); PG8_STAGE(PG8_SB(0, 1), cB + hstep, voffB); PG8_STAGE(PG8_SA(0, 0), cA, voffA); PG8_STAGE(PG8_SA(0, 1), cA + hstep, voffA);
;         if (wr == 1) PG8_BAR;
;         PG8_WAIT_V(2); PG8_BAR;
;         PG8_STAGE(PG8_SB(1, 0), cB + kstep, voffB); PG8_STAGE(PG8_SA(1, 0), cA + kstep, voffA); PG8_STAGE(PG8_SB(1, 1), cB + hstep + kstep, voffB);
;         PG8_WAIT_V(6); PG8_BAR;
;     } else {
;         PG8_STAGE(PG8_SB(0, 0), cB, voffB); PG8_STAGE(PG8_SA(0, 0), cA, voffA); PG8_STAGE(PG8_SB(0, 1), cB + hstep, voffB); PG8_STAGE(PG8_SA(0, 1), cA + hstep, voffA);
;         if (wr == 1) PG8_BAR;
;         PG8_WAIT_V(4); PG8_BAR;
; __global__ void __launch_bounds__(NWAVES * 64, 2) fwd_kernel(Args a) {
;     ...
;     if (IN(6)) for (int rep = 0; rep < NREP(6); ++rep) {
;         pg8::Gemm g{OG, WT4, NTOK, DM, DM}; pg8::StaticOrder S; S.init(NTOK, DM, G, bx);
;         pg8::EpiFinal E{H1B, final_g, a.out, HSS2, CNT, G == 256};
;         pg8::gemm_phase<pg8::EpiFinal, pg8::StaticOrder, GEMM_ALIGN, GEMM_SP2>(lds, g, S, E, wave);
.LBB0_687:
	s_andn2_b64 vcc, exec, s[0:1]
	s_cbranch_vccnz .LBB0_742
	s_cmpk_lg_i32 s88, 0x100
	s_cbranch_scc1 .Lp6_nowait
	s_lshl_b32 s98, s28, 8
	s_add_i32 s98, s98, 4
	v_mov_b32_e32 v236, s98
	s_add_u32 s98, s82, 0x310000
	s_addc_u32 s99, s83, 0
	s_mov_b32 s100, 0
.Lp6_poll:
	global_load_dword v237, v236, s[98:99] sc1
	s_waitcnt vmcnt(0)
	v_readfirstlane_b32 s101, v237
	s_cmpk_ge_u32 s101, 0x80
	s_cbranch_scc1 .Lp6_ready
	s_add_i32 s100, s100, 1
	s_cmp_lt_u32 s100, 0x10000
	s_cbranch_scc0 .Lp6_ready
	s_sleep 2
	s_branch .Lp6_poll
.Lp6_ready:
.Lp6_nowait:
	v_readlane_b32 s1, v248, 22
	s_lshl_b32 s2, s1, 10
	v_lshl_add_u32 v0, v195, 4, s2
	s_waitcnt lgkmcnt(0)
	v_ashrrev_i32_e32 v1, 31, v0
	v_lshrrev_b32_e32 v1, 22, v1
	v_add_u32_e32 v1, v0, v1
	v_ashrrev_i32_e32 v8, 10, v1
	v_mul_i32_i24_e32 v1, 0x400, v8
	v_sub_u32_e32 v1, v0, v1
	v_lshrrev_b32_e32 v2, 4, v1
	v_bitop3_b32 v1, v2, v1, 32 bitop3:0x6c
	v_ashrrev_i32_e32 v3, 31, v1
	v_lshrrev_b32_e32 v3, 26, v3
	v_add_u32_e32 v3, v1, v3
	v_lshlrev_b32_e32 v2, 3, v8
	v_ashrrev_i32_e32 v9, 6, v3
	v_and_b32_e32 v3, 0xc0, v3
	v_and_b32_e32 v2, -16, v2
	v_sub_u32_e32 v1, v1, v3
	v_mov_b32_e32 v3, 1
	v_add_u32_e32 v2, v9, v2
	v_ashrrev_i16_sdwa v1, v3, sext(v1) dst_sel:DWORD dst_unused:UNUSED_PAD src0_sel:DWORD src1_sel:BYTE_0
	v_lshlrev_b32_e32 v4, 5, v8
	v_bfe_i32 v10, v1, 0, 16
	v_lshlrev_b32_e32 v1, 1, v2
	v_lshrrev_b32_e32 v5, 2, v2
	v_and_b32_e32 v6, 3, v9
	s_mov_b32 s1, 0xfffe0
	v_and_b32_e32 v4, 32, v4
	v_and_b32_e32 v1, 24, v1
	v_and_b32_e32 v5, 4, v5
	v_and_or_b32 v6, v2, s1, v6
	v_or3_b32 v1, v6, v5, v1
	v_add_lshl_u32 v4, v4, v10, 1
	v_add_u32_e32 v0, 0x2000, v0
	v_lshl_add_u32 v146, v1, 12, v4
	v_ashrrev_i32_e32 v1, 31, v0
	v_lshrrev_b32_e32 v1, 22, v1
	v_add_u32_e32 v1, v0, v1
	v_ashrrev_i32_e32 v11, 10, v1
	v_mul_i32_i24_e32 v1, 0x400, v11
	v_sub_u32_e32 v0, v0, v1
	v_lshrrev_b32_e32 v1, 4, v0
	v_bitop3_b32 v0, v1, v0, 32 bitop3:0x6c
	v_lshl_add_u32 v144, v2, 12, v4
	v_ashrrev_i32_e32 v2, 31, v0
	v_lshrrev_b32_e32 v2, 26, v2
	v_add_u32_e32 v2, v0, v2
	v_ashrrev_i32_e32 v12, 6, v2
	v_and_b32_e32 v2, 0xffc0, v2
	s_lshr_b32 s0, s67, 8
	v_sub_u32_e32 v0, v0, v2
	v_lshrrev_b16_e32 v2, 7, v0
	s_cmp_eq_u32 s0, 1
	v_lshlrev_b32_e32 v1, 3, v11
	v_and_b32_e32 v2, 1, v2
	s_cselect_b64 s[10:11], -1, 0
	s_ashr_i32 s29, s28, 31
	s_ashr_i32 s31, s30, 31
	v_and_b32_e32 v1, -16, v1
	v_add_u16_e32 v0, v0, v2
	s_lshl_b64 s[4:5], s[28:29], 20
	s_lshl_b64 s[6:7], s[30:31], 20
	v_add_u32_e32 v1, v12, v1
	v_ashrrev_i16_sdwa v0, v3, sext(v0) dst_sel:DWORD dst_unused:UNUSED_PAD src0_sel:DWORD src1_sel:BYTE_0
	s_add_u32 s36, s62, s6
	v_lshlrev_b32_e32 v4, 5, v11
	v_bfe_i32 v13, v0, 0, 16
	v_lshlrev_b32_e32 v0, 1, v1
	v_lshrrev_b32_e32 v2, 2, v1
	v_and_b32_e32 v3, 3, v12
	s_addc_u32 s37, s63, s7
	s_add_i32 s42, s2, 0
	v_and_b32_e32 v4, 32, v4
	v_and_b32_e32 v0, 24, v0
	v_and_b32_e32 v2, 4, v2
	v_and_or_b32 v3, v1, s1, v3
	s_add_i32 m0, s42, 0x10000
	s_add_i32 s1, s42, 0x12000
	v_or3_b32 v0, v3, v2, v0
	v_add_lshl_u32 v2, v4, v13, 1
	s_add_u32 s6, s36, 0x80000
	v_lshl_add_u32 v150, v0, 12, v2
	s_addc_u32 s7, s37, 0
	s_add_i32 s12, s42, 0x14000
	s_add_i32 s13, s42, 0x16000
	v_readlane_b32 s14, v248, 25
	global_load_lds_dwordx4 v146, s[36:37]
	s_mov_b32 m0, s1
	v_readlane_b32 s15, v248, 26
	s_add_u32 s34, s14, s4
	global_load_lds_dwordx4 v150, s[36:37]
	s_mov_b32 m0, s12
	s_addc_u32 s35, s15, s5
	s_add_i32 s43, s42, 0x2000
	global_load_lds_dwordx4 v146, s[6:7]
	s_mov_b32 m0, s13
	s_add_u32 s4, s34, 0x80000
	global_load_lds_dwordx4 v150, s[6:7]
	s_mov_b32 m0, s42
	v_lshl_add_u32 v148, v1, 12, v2
	s_addc_u32 s5, s35, 0
	s_add_i32 s44, s42, 0x4000
	global_load_lds_dwordx4 v144, s[34:35]
	s_mov_b32 m0, s43
	s_add_i32 s45, s42, 0x6000
	global_load_lds_dwordx4 v148, s[34:35]
	s_mov_b32 m0, s44
	v_mov_b32_e32 v147, 0
	global_load_lds_dwordx4 v144, s[4:5]
	s_mov_b32 m0, s45
	v_mov_b32_e32 v151, v147
	global_load_lds_dwordx4 v148, s[4:5]
	v_mov_b32_e32 v145, v147
	v_mov_b32_e32 v149, v147
	s_mov_b32 s46, 0
	s_cmp_lg_u32 s0, 1
	v_lshl_add_u64 v[6:7], s[36:37], 0, v[146:147]
	v_lshl_add_u64 v[4:5], s[36:37], 0, v[150:151]
	v_lshl_add_u64 v[2:3], s[34:35], 0, v[144:145]
	v_lshl_add_u64 v[0:1], s[34:35], 0, v[148:149]
	s_cbranch_scc1 .LBB0_690
	s_barrier
